# v13: v12 + ret scan: next chunk's Q/K stage ds_writes moved from loop top to the O-section tail (after barrier 2), entry-only ladder for chunk 0
# baseline (speedup 1.0000x reference)
;     ...
;             mx_bf16x8 aq[KS];
;             if (do_out) {
; #pragma unroll
;                 for (int ks = 0; ks < KS; ++ks) aq[ks] = frag_row(L, QS, nq0, 32 * ks, lane);
;                 for (int rep1 = 0; rep1 < MXP_S1; ++rep1) {
;                 f32x4 pt0 = ZERO4, pt1 = ZERO4;
; #pragma unroll
;                 for (int kb = 0; kb < KS; kb += 4) {
;                     mx_bf16x8 kf[2][4];
; #pragma unroll
;                     for (int ks = 0; ks < 4; ++ks) { kf[0][ks] = frag_row(L + IMG, QS, 32 * cg, 32 * (kb + ks), lane); kf[1][ks] = frag_row(L + IMG, QS, 32 * cg + 16, 32 * (kb + ks), lane); }
;                     __builtin_amdgcn_sched_barrier(0);
; #pragma unroll
;                     for (int ks = 0; ks < 4; ++ks) { pt0 = MX_MFMA(kf[0][ks], aq[kb + ks], pt0); pt1 = MX_MFMA(kf[1][ks], aq[kb + ks], pt1); }
;                     __builtin_amdgcn_sched_barrier(0);
;                 }
;                 const int m0 = 32 * cg + 4 * g, n = nq0 + i;
;                 v2u pw; pw.x = pk2((m0 <= n) ? pt0[0] : 0.f, (m0 + 1 <= n) ? pt0[1] : 0.f); pw.y = pk2((m0 + 2 <= n) ? pt0[2] : 0.f, (m0 + 3 <= n) ? pt0[3] : 0.f);
;                 *(LAS v2u*)(L + O_P + n * PS + 16 * ((m0 >> 3) ^ sw8(n)) + (m0 & 7) * 2) = pw;
;                 const int m1 = m0 + 16;
;                 pw.x = pk2((m1 <= n) ? pt1[0] : 0.f, (m1 + 1 <= n) ? pt1[1] : 0.f); pw.y = pk2((m1 + 2 <= n) ? pt1[2] : 0.f, (m1 + 3 <= n) ? pt1[3] : 0.f);
;                 *(LAS v2u*)(L + O_P + n * PS + 16 * ((m1 >> 3) ^ sw8(n)) + (m1 & 7) * 2) = pw;
;                 }
;             }
;             {
;                 mx_bf16x8 vt[4][2], ak[DT][2]; f32x4 dec[DT];
; #pragma unroll
;                 for (int te = 0; te < 4; ++te) { vt[te][0] = frag_row8(L + O_VT, 16 * te, 0, lane); vt[te][1] = frag_row8(L + O_VT, 16 * te, 32, lane); }
; #pragma unroll
;                 for (int td = 0; td < DT; ++td) { const int d0 = 16 * (DT * w + td);
;                     ak[td][0] = frag_tr(L + (HG ? 3 : 1) * IMG, QS, 0, d0, lane); ak[td][1] = frag_tr(L + (HG ? 3 : 1) * IMG, QS, 32, d0, lane);
;                     dec[td] = (f32x4){cdec, cdec, cdec, cdec};
;                     if (HG) { const f32x4 ce = *(const LAS f32x4*)(L + O_TOT + 2048 + (d0 + 4 * g) * 4); dec[td] = (f32x4){__expf(ce[0]), __expf(ce[1]), __expf(ce[2]), __expf(ce[3])}; } }
;                 __builtin_amdgcn_sched_barrier(0);
; #pragma unroll
.LBB0_798:
	s_waitcnt vmcnt(0)
	v_lshlrev_b32_e32 v6, 16, v58
	v_and_b32_e32 v7, 0xffff0000, v58
	v_pk_mul_f32 v[6:7], v[136:137], v[6:7]
	v_cvt_pk_bf16_f32 v6, v6, v7
	ds_write_b16 v177, v6
	ds_write_b16_d16_hi v187, v6 offset:160
	v_lshlrev_b32_e32 v6, 16, v59
	v_and_b32_e32 v7, 0xffff0000, v59
	v_pk_mul_f32 v[6:7], v[136:137], v[6:7]
	v_add_u32_e32 v34, v152, v117
	v_cvt_pk_bf16_f32 v6, v6, v7
	ds_write_b16 v177, v6 offset:320
	ds_write_b16_d16_hi v186, v6 offset:160
	v_lshlrev_b32_e32 v6, 16, v60
	v_and_b32_e32 v7, 0xffff0000, v60
	v_pk_mul_f32 v[6:7], v[136:137], v[6:7]
	s_and_b64 s[24:25], s[24:25], exec
	v_cvt_pk_bf16_f32 v6, v6, v7
	ds_write_b16 v177, v6 offset:640
	ds_write_b16_d16_hi v185, v6 offset:160
	v_lshlrev_b32_e32 v6, 16, v61
	v_and_b32_e32 v7, 0xffff0000, v61
	v_pk_mul_f32 v[6:7], v[136:137], v[6:7]
	v_add_u32_e32 v136, v153, v117
	v_cvt_pk_bf16_f32 v6, v6, v7
	ds_write_b16 v177, v6 offset:960
	ds_write_b16_d16_hi v184, v6 offset:160
	s_waitcnt lgkmcnt(0)
	s_barrier
	ds_read_b128 v[6:9], v34
	ds_read_b128 v[10:13], v34 offset:64
	ds_read_b128 v[14:17], v34 offset:128
	ds_read_b128 v[18:21], v34 offset:192
	ds_read_b128 v[22:25], v34 offset:256
	ds_read_b128 v[26:29], v34 offset:320
	ds_read_b128 v[30:33], v34 offset:384
	ds_read_b128 v[34:37], v34 offset:448
	ds_read_b128 v[58:61], v136 offset:34816
	ds_read_b128 v[66:69], v136 offset:34880
	ds_read_b128 v[74:77], v136 offset:43520
	ds_read_b128 v[78:81], v136 offset:43584
	ds_read_b128 v[86:89], v136 offset:34944
	ds_read_b128 v[90:93], v136 offset:35008
	ds_read_b128 v[94:97], v136 offset:43648
	ds_read_b128 v[98:101], v136 offset:43712
	s_cselect_b32 s24, 0xfc0, 0
	s_or_b32 s24, s24, s30
	s_waitcnt lgkmcnt(7)
	v_mfma_f32_16x16x32_bf16 v[58:61], v[58:61], v[6:9], v[2:5]
	s_waitcnt lgkmcnt(5)
	v_mfma_f32_16x16x32_bf16 v[74:77], v[74:77], v[6:9], v[2:5]
	v_mfma_f32_16x16x32_bf16 v[58:61], v[66:69], v[10:13], v[58:61]
	s_waitcnt lgkmcnt(4)
	v_mfma_f32_16x16x32_bf16 v[66:69], v[78:81], v[10:13], v[74:77]
	s_waitcnt lgkmcnt(3)
	v_mfma_f32_16x16x32_bf16 v[58:61], v[86:89], v[14:17], v[58:61]
	s_waitcnt lgkmcnt(1)
	v_mfma_f32_16x16x32_bf16 v[66:69], v[94:97], v[14:17], v[66:69]
	v_mfma_f32_16x16x32_bf16 v[58:61], v[90:93], v[18:21], v[58:61]
	s_waitcnt lgkmcnt(0)
	v_mfma_f32_16x16x32_bf16 v[66:69], v[98:101], v[18:21], v[66:69]
	ds_read_b128 v[74:77], v136 offset:35072
	ds_read_b128 v[78:81], v136 offset:35136
	ds_read_b128 v[86:89], v136 offset:43776
	ds_read_b128 v[90:93], v136 offset:43840
	ds_read_b128 v[94:97], v136 offset:35200
	ds_read_b128 v[98:101], v136 offset:35264
	ds_read_b128 v[102:105], v136 offset:43904
	ds_read_b128 v[136:139], v136 offset:43968
	s_waitcnt lgkmcnt(7)
	v_mfma_f32_16x16x32_bf16 v[58:61], v[74:77], v[22:25], v[58:61]
	s_waitcnt lgkmcnt(5)
	v_mfma_f32_16x16x32_bf16 v[66:69], v[86:89], v[22:25], v[66:69]
	v_mfma_f32_16x16x32_bf16 v[58:61], v[78:81], v[26:29], v[58:61]
	s_waitcnt lgkmcnt(4)
	v_mfma_f32_16x16x32_bf16 v[66:69], v[90:93], v[26:29], v[66:69]
	s_waitcnt lgkmcnt(3)
	v_mfma_f32_16x16x32_bf16 v[58:61], v[94:97], v[30:33], v[58:61]
	s_waitcnt lgkmcnt(1)
	v_mfma_f32_16x16x32_bf16 v[66:69], v[102:105], v[30:33], v[66:69]
	v_mfma_f32_16x16x32_bf16 v[58:61], v[98:101], v[34:37], v[58:61]
	s_waitcnt lgkmcnt(0)
	v_mfma_f32_16x16x32_bf16 v[66:69], v[136:139], v[34:37], v[66:69]
	s_nop 5
	v_cndmask_b32_e64 v58, v58, 0, s[8:9]
	v_cndmask_b32_e64 v59, 0, v59, s[10:11]
	v_cvt_pk_bf16_f32 v58, v58, v59
	v_cndmask_b32_e64 v59, v60, 0, s[12:13]
	v_cndmask_b32_e64 v60, v61, 0, s[14:15]
	v_cvt_pk_bf16_f32 v59, v59, v60
	v_add_u32_e32 v60, v158, v148
	ds_write_b64 v60, v[58:59]
	v_cndmask_b32_e64 v58, v66, 0, s[16:17]
	v_cndmask_b32_e64 v59, v67, 0, s[18:19]
	v_cvt_pk_bf16_f32 v58, v58, v59
	v_cndmask_b32_e64 v59, v68, 0, s[20:21]
	v_cndmask_b32_e64 v60, v69, 0, s[22:23]
	v_cvt_pk_bf16_f32 v59, v59, v60
	v_add_u32_e32 v60, v159, v148
	ds_write_b64 v60, v[58:59]
	ds_read_b128 v[58:61], v192
	ds_read_b128 v[66:69], v192 offset:64
	ds_read_b128 v[74:77], v171
	ds_read_b128 v[78:81], v171 offset:64
	ds_read_b128 v[86:89], v172
	ds_read_b128 v[90:93], v172 offset:64
	ds_read_b128 v[94:97], v173
	ds_read_b128 v[98:101], v173 offset:64
	ds_read_b64_tr_b16 v[102:103], v174 offset:34816
	ds_read_b64_tr_b16 v[104:105], v174 offset:36992
	ds_read_b64_tr_b16 v[138:139], v174 offset:37024
	ds_read_b64_tr_b16 v[136:137], v174 offset:34848
	ds_read_b64_tr_b16 v[140:141], v174 offset:52224
	ds_read_b64_tr_b16 v[142:143], v174 offset:54400
	ds_read_b64_tr_b16 v[146:147], v174 offset:54432
	ds_read_b64_tr_b16 v[144:145], v174 offset:52256
	v_pk_mul_f32 v[64:65], v[134:135], v[64:65]
	v_pk_mul_f32 v[62:63], v[130:131], v[62:63]
	v_pk_mul_f32 v[44:45], v[134:135], v[44:45]
	v_pk_mul_f32 v[42:43], v[130:131], v[42:43]
	v_pk_mul_f32 v[84:85], v[134:135], v[84:85]
	v_pk_mul_f32 v[82:83], v[130:131], v[82:83]
	v_pk_mul_f32 v[72:73], v[134:135], v[72:73]
	v_pk_mul_f32 v[70:71], v[130:131], v[70:71]
	s_waitcnt lgkmcnt(6)
	v_mfma_f32_16x16x32_bf16 v[62:65], v[102:105], v[86:89], v[62:65]
	v_mul_f32_e64 v56, v134, v56
	v_mul_f32_e64 v57, v135, v57
	v_pk_mul_f32 v[54:55], v[130:131], v[54:55]
	v_pk_mul_f32 v[52:53], v[134:135], v[52:53]
	v_pk_mul_f32 v[50:51], v[130:131], v[50:51]
	v_pk_mul_f32 v[48:49], v[134:135], v[48:49]
	v_pk_mul_f32 v[46:47], v[130:131], v[46:47]
	s_waitcnt lgkmcnt(4)
	v_mfma_f32_16x16x32_bf16 v[42:45], v[136:139], v[86:89], v[42:45]
	v_mul_f32_e64 v40, v134, v40
	v_mul_f32_e64 v41, v135, v41
	v_pk_mul_f32 v[38:39], v[130:131], v[38:39]
	s_waitcnt lgkmcnt(0)
	v_mfma_f32_16x16x32_bf16 v[82:85], v[102:105], v[58:61], v[82:85]
	s_barrier
;     ...
;             MX_BAR();
;             if (do_out) {
;                 if (HG) {
; #pragma unroll
;                     for (int ks = 0; ks < KS; ++ks) aq[ks] = frag_row(L + 2 * IMG, QS, nq0, 32 * ks, lane);
;                 }
;                 mx_bf16x8 vo[2][2];
;                 const mx_bf16x8 bp0 = frag_row8(L + O_P, nq0, 0, lane), bp1 = frag_row8(L + O_P, nq0, 32, lane);
; #pragma unroll
;                 for (int te = 0; te < 2; ++te) { vo[te][0] = frag_row8(L + O_VT, 32 * cg + 16 * te, 0, lane); vo[te][1] = frag_row8(L + O_VT, 32 * cg + 16 * te, 32, lane); }
;                 const int grow = rlo + (dir ? 63 - (nq0 + i) : (nq0 + i));
;                 for (int rep2 = 0; rep2 < MXP_S2; ++rep2) {
;                 f32x4 o1a = ZERO4, o1b = o1a, o2a = o1a, o2b = o1a;
; #pragma unroll
;                 for (int kb = 0; kb < KS; kb += 4) {
;                     mx_bf16x8 st[2][4];
; #pragma unroll
;                     for (int ks = 0; ks < 4; ++ks) { st[0][ks] = frag_row(L + O_ST, QS, 32 * cg, 32 * (kb + ks), lane); st[1][ks] = frag_row(L + O_ST, QS, 32 * cg + 16, 32 * (kb + ks), lane); }
;                     __builtin_amdgcn_sched_barrier(0);
;                     if (kb == 0) { o1a = MX_MFMA(vo[0][0], bp0, o1a); o1b = MX_MFMA(vo[1][0], bp0, o1b); o1a = MX_MFMA(vo[0][1], bp1, o1a); o1b = MX_MFMA(vo[1][1], bp1, o1b); }
; #pragma unroll
;                     for (int ks = 0; ks < 4; ++ks) { o2a = MX_MFMA(st[0][ks], aq[kb + ks], o2a); o2b = MX_MFMA(st[1][ks], aq[kb + ks], o2b); }
;                     __builtin_amdgcn_sched_barrier(0);
;                 }
;                 bf16* op = O + (size_t)grow * D + h * HD + eb * 64 + 32 * cg + 4 * g;
;                 if (!(VAR & 2)) { const f32x4 ya = o1a * r1 + o2a * r2, yb = o1b * r1 + o2b * r2; v2u wa, wb; wa.x = pk2(ya[0], ya[1]); wa.y = pk2(ya[2], ya[3]); wb.x = pk2(yb[0], yb[1]); wb.y = pk2(yb[2], yb[3]);
;                     *(GAS v2u*)(op) = wa; *(GAS v2u*)(op + 16) = wb; }
;                 else { asm volatile("" :: "v"(o1a), "v"(o1b), "v"(o2a), "v"(o2b)); }
;                 }
;             }
;             MX_BAR();
; #pragma unroll
;             for (int td = 0; td < DT; ++td)
; #pragma unroll
;                 for (int te = 0; te < 4; ++te) { const int d0 = 16 * (DT * w + td); const f32x4 s = accS[td][te];
;                     v2u sw; sw.x = pk2(s[0], s[1]); sw.y = pk2(s[2], s[3]);
	v_mfma_f32_16x16x32_bf16 v[70:73], v[102:105], v[74:77], v[70:73]
	v_mfma_f32_16x16x32_bf16 v[54:57], v[102:105], v[94:97], v[54:57]
	v_mfma_f32_16x16x32_bf16 v[50:53], v[136:139], v[58:61], v[50:53]
	v_mfma_f32_16x16x32_bf16 v[46:49], v[136:139], v[74:77], v[46:49]
	v_add_u32_e32 v74, v154, v117
	v_mfma_f32_16x16x32_bf16 v[38:41], v[136:139], v[94:97], v[38:41]
	v_add_u32_e32 v94, s24, v176
	v_ashrrev_i32_e32 v95, 31, v94
	v_lshlrev_b64 v[94:95], 12, v[94:95]
	s_waitcnt lgkmcnt(2)
	v_mfma_f32_16x16x32_bf16 v[62:65], v[140:143], v[90:93], v[62:65]
	v_add_u32_e32 v176, v155, v117
	s_waitcnt lgkmcnt(0)
	v_mfma_f32_16x16x32_bf16 v[42:45], v[144:147], v[90:93], v[42:45]
	v_add_u32_e32 v90, v168, v117
	v_mfma_f32_16x16x32_bf16 v[58:61], v[140:143], v[66:69], v[82:85]
	v_mfma_f32_16x16x32_bf16 v[70:73], v[140:143], v[78:81], v[70:73]
	v_mfma_f32_16x16x32_bf16 v[54:57], v[140:143], v[98:101], v[54:57]
	v_mfma_f32_16x16x32_bf16 v[50:53], v[144:147], v[66:69], v[50:53]
	ds_read_b128 v[66:69], v74
	ds_read_b128 v[74:77], v74 offset:64
	v_mfma_f32_16x16x32_bf16 v[46:49], v[144:147], v[78:81], v[46:49]
	ds_read_b128 v[78:81], v90
	ds_read_b128 v[82:85], v90 offset:64
	ds_read_b128 v[86:89], v90 offset:2560
	ds_read_b128 v[90:93], v90 offset:2624
	v_mfma_f32_16x16x32_bf16 v[38:41], v[144:147], v[98:101], v[38:41]
	v_lshl_add_u64 v[146:147], v[132:133], 0, v[94:95]
	ds_read_b128 v[94:97], v176
	ds_read_b128 v[98:101], v176 offset:8704
	ds_read_b128 v[102:105], v176 offset:64
	ds_read_b128 v[130:133], v176 offset:8768
	ds_read_b128 v[134:137], v176 offset:128
	ds_read_b128 v[138:141], v176 offset:8832
	ds_read_b128 v[142:145], v176 offset:192
	ds_read_b128 v[184:187], v176 offset:8896
	s_waitcnt lgkmcnt(11)
	v_mfma_f32_16x16x32_bf16 v[78:81], v[78:81], v[66:69], v[2:5]
	s_waitcnt lgkmcnt(9)
	v_mfma_f32_16x16x32_bf16 v[66:69], v[86:89], v[66:69], v[2:5]
	v_mfma_f32_16x16x32_bf16 v[78:81], v[82:85], v[74:77], v[78:81]
	s_waitcnt lgkmcnt(8)
	v_mfma_f32_16x16x32_bf16 v[66:69], v[90:93], v[74:77], v[66:69]
	s_waitcnt lgkmcnt(7)
	v_mfma_f32_16x16x32_bf16 v[74:77], v[94:97], v[6:9], v[2:5]
	s_waitcnt lgkmcnt(6)
	v_mfma_f32_16x16x32_bf16 v[82:85], v[98:101], v[6:9], v[2:5]
	s_waitcnt lgkmcnt(5)
	v_mfma_f32_16x16x32_bf16 v[74:77], v[102:105], v[10:13], v[74:77]
	s_waitcnt lgkmcnt(4)
	v_mfma_f32_16x16x32_bf16 v[82:85], v[130:133], v[10:13], v[82:85]
	s_waitcnt lgkmcnt(3)
	v_mfma_f32_16x16x32_bf16 v[74:77], v[134:137], v[14:17], v[74:77]
	s_waitcnt lgkmcnt(2)
	v_mfma_f32_16x16x32_bf16 v[82:85], v[138:141], v[14:17], v[82:85]
	s_waitcnt lgkmcnt(1)
	v_mfma_f32_16x16x32_bf16 v[74:77], v[142:145], v[18:21], v[74:77]
	s_waitcnt lgkmcnt(0)
	v_mfma_f32_16x16x32_bf16 v[82:85], v[184:187], v[18:21], v[82:85]
	ds_read_b128 v[86:89], v176 offset:256
	ds_read_b128 v[90:93], v176 offset:320
	ds_read_b128 v[94:97], v176 offset:8960
	ds_read_b128 v[98:101], v176 offset:9024
	ds_read_b128 v[102:105], v176 offset:384
	ds_read_b128 v[130:133], v176 offset:448
	ds_read_b128 v[134:137], v176 offset:9088
	ds_read_b128 v[138:141], v176 offset:9152
	s_waitcnt lgkmcnt(7)
	v_mfma_f32_16x16x32_bf16 v[74:77], v[86:89], v[22:25], v[74:77]
	s_waitcnt lgkmcnt(5)
	v_mfma_f32_16x16x32_bf16 v[82:85], v[94:97], v[22:25], v[82:85]
	v_mfma_f32_16x16x32_bf16 v[74:77], v[90:93], v[26:29], v[74:77]
	s_waitcnt lgkmcnt(4)
	v_mfma_f32_16x16x32_bf16 v[82:85], v[98:101], v[26:29], v[82:85]
	s_waitcnt lgkmcnt(3)
	v_mfma_f32_16x16x32_bf16 v[74:77], v[102:105], v[30:33], v[74:77]
	s_waitcnt lgkmcnt(1)
	v_mfma_f32_16x16x32_bf16 v[82:85], v[134:137], v[30:33], v[82:85]
	v_mfma_f32_16x16x32_bf16 v[74:77], v[130:133], v[34:37], v[74:77]
	s_waitcnt lgkmcnt(0)
	v_mfma_f32_16x16x32_bf16 v[82:85], v[138:141], v[34:37], v[82:85]
	s_nop 5
	v_mul_f32_e64 v76, v128, v76
	v_mul_f32_e64 v77, v129, v77
	v_pk_mul_f32 v[74:75], v[124:125], v[74:75]
	v_pk_fma_f32 v[76:77], v[126:127], v[80:81], v[76:77]
	v_pk_fma_f32 v[74:75], v[122:123], v[78:79], v[74:75]
	v_pk_mul_f32 v[78:79], v[128:129], v[84:85]
	v_pk_mul_f32 v[80:81], v[124:125], v[82:83]
	v_pk_fma_f32 v[68:69], v[126:127], v[68:69], v[78:79]
	v_pk_fma_f32 v[66:67], v[122:123], v[66:67], v[80:81]
	v_cvt_pk_bf16_f32 v74, v74, v75
	v_cvt_pk_bf16_f32 v75, v76, v77
	v_cvt_pk_bf16_f32 v66, v66, v67
	v_cvt_pk_bf16_f32 v67, v68, v69
	global_store_dwordx2 v[146:147], v[74:75], off
	global_store_dwordx2 v[146:147], v[66:67], off offset:32
	s_waitcnt lgkmcnt(0)
	s_barrier
	s_add_i32 s44, s44, s3
	v_cvt_pk_bf16_f32 v58, v58, v59
	v_cvt_pk_bf16_f32 v59, v60, v61
	v_cvt_pk_bf16_f32 v60, v70, v71
	v_cvt_pk_bf16_f32 v61, v72, v73
	v_cvt_pk_bf16_f32 v62, v62, v63
	v_cvt_pk_bf16_f32 v63, v64, v65
	v_cvt_pk_bf16_f32 v54, v54, v55
	v_cvt_pk_bf16_f32 v55, v56, v57
	v_cvt_pk_bf16_f32 v50, v50, v51
	v_cvt_pk_bf16_f32 v51, v52, v53
	v_cvt_pk_bf16_f32 v46, v46, v47
	v_cvt_pk_bf16_f32 v47, v48, v49
	v_cvt_pk_bf16_f32 v42, v42, v43
	v_cvt_pk_bf16_f32 v43, v44, v45
	v_cvt_pk_bf16_f32 v38, v38, v39
	v_cvt_pk_bf16_f32 v39, v40, v41
	s_cmpk_gt_i32 s44, 0xff
	ds_write2_b64 v175, v[58:59], v[50:51] offset1:4
	ds_write2_b64 v193, v[60:61], v[46:47] offset0:64 offset1:68
	ds_write2_b64 v194, v[62:63], v[42:43] offset0:128 offset1:132
	ds_write2_b64 v195, v[54:55], v[38:39] offset0:192 offset1:196
	s_cbranch_scc1 .LBB0_809

; #define LAS __attribute__((address_space(3)))
;     ...
;         const int eb = task % NEB, dir = (task / NEB) & 1, h = (task / (2 * NEB)) % NH, b = task / (2 * NEB * NH);
;         bf16* O = (bf16*)(a.ws + (dir ? WS_OB : WS_OF));
;         const bf16* src0 = act;
;         const bf16* src1 = act + (size_t)(HG ? (2 + 2 * dir) : 1) * ACT_STRIDE;
;         const bf16* src2 = act + (size_t)(1 + 2 * dir) * ACT_STRIDE;
;         const bf16* srcv = act + (size_t)(HG ? 5 : 2) * ACT_STRIDE;
;         float lg2 = 0.f;
;         if (!HG) { const float x = a.in[10][(j_layer * 2 + dir) * 8 + h]; lg2 = -log1pf(expf(-x)) * 1.4426950408889634f; }
;         const float r1 = HG ? 1.f : exp2f((float)(nq0 + i - 63) * lg2), r2 = HG ? 1.f : exp2f((float)(nq0 + i + 1) * lg2), cdec = HG ? 1.f : exp2f(64.f * lg2);
;         const int vrow = tid & 63, vcc = tid >> 6;
;         const int vs = dir ? 63 - vrow : vrow;
;         const float kdec = HG ? 1.f : exp2f((float)(63 - vs) * lg2);
;         f32x4 accS[DT][4];
; #pragma unroll
;         for (int td = 0; td < DT; ++td)
; #pragma unroll
;             for (int te = 0; te < 4; ++te) accS[td][te] = ZERO4;
;         constexpr int NPQ = HG ? 2 : 4;
;         constexpr int PF = HG ? MX_PF_HG : MX_PF_RET;
;         static_assert(NCH % PF == 0, "prefetch depth must divide the chunk count");
;         v4u rq[PF][HG ? 3 : 2][NPQ]; v4u rv[PF];
;     ...
;         __syncthreads();
;         for (int u = tid; u < IMG / 16; u += NWAVES * 64) { const unsigned zu_ = __builtin_bit_cast(unsigned, zf_); *(LAS v4u*)(L + O_ST + u * 16) = (v4u){zu_, zu_, zu_, zu_}; }
; #pragma unroll
;         for (int u = 0; u < PF; ++u) MX_LOAD(u, u);
;         for (int c0 = 0; c0 < NCH; c0 += PF)
; #pragma unroll
;         for (int u = 0; u < PF; ++u) {
;             const int c = c0 + u;
;             MX_STAGE(u);
.LBB0_802:
	s_or_b64 exec, exec, s[36:37]
	v_mov_b32_e32 v46, 0x42800000
	v_cndmask_b32_e64 v43, 0, v46, s[30:31]
	v_fmac_f32_e32 v43, v40, v150
	v_cndmask_b32_e64 v44, 0, v46, s[28:29]
	v_exp_f32_e32 v43, v43
	v_fmac_f32_e32 v44, v40, v151
	v_exp_f32_e32 v44, v44
	v_not_b32_e32 v47, 63
	v_cndmask_b32_e64 v45, 0, v47, s[30:31]
	v_ldexp_f32 v122, v43, v45
	v_cndmask_b32_e64 v43, 0, v47, s[28:29]
	v_ldexp_f32 v124, v44, v43
	v_cndmask_b32_e32 v44, 0, v46, vcc
	v_cndmask_b32_e64 v43, 0, v46, s[26:27]
	v_fmac_f32_e32 v44, v40, v42
	v_cndmask_b32_e64 v42, 0, v47, s[26:27]
	s_and_b64 s[26:27], s[24:25], exec
	s_mov_b32 s26, 0x2ac00000
	s_cselect_b32 s26, s26, 0x33400000
	s_lshl_b32 s28, s51, 2
	s_sub_i32 s30, s44, s28
	s_lshr_b32 s28, s48, 26
	s_add_i32 s28, s44, s28
	v_fmac_f32_e32 v43, 0x42800000, v40
	s_mov_b32 s27, 0
	s_ashr_i32 s40, s28, 6
	v_exp_f32_e32 v43, v43
	v_lshl_add_u64 v[38:39], v[38:39], 0, s[26:27]
	s_lshl_b32 s26, s40, 8
	v_exp_f32_e32 v40, v44
	s_addk_i32 s26, 0x4000
	s_and_b64 s[28:29], s[24:25], exec
	s_cselect_b32 s28, 0, 0xc0
	v_ldexp_f32 v130, v43, v42
	v_cndmask_b32_e32 v42, 0, v47, vcc
	s_or_b32 s41, s28, s26
	v_ldexp_f32 v136, v40, v42
	v_or_b32_e32 v42, s41, v113
	s_lshl_b32 s28, s49, 8
	v_ashrrev_i32_e32 v43, 31, v42
	v_lshlrev_b64 v[42:43], 12, v[42:43]
	s_ashr_i32 s29, s28, 31
	s_lshl_b32 s30, s30, 6
	v_add_u32_e32 v44, s41, v149
	v_lshl_add_u64 v[42:43], v[110:111], 0, v[42:43]
	s_lshl_b64 s[34:35], s[28:29], 1
	s_ashr_i32 s31, s30, 31
	v_ashrrev_i32_e32 v45, 31, v44
	v_add_u32_e32 v138, s28, v157
	v_lshl_add_u64 v[42:43], v[42:43], 0, s[34:35]
	s_lshl_b64 s[36:37], s[30:31], 1
	v_lshlrev_b64 v[44:45], 11, v[44:45]
	v_ashrrev_i32_e32 v139, 31, v138
	v_lshl_add_u64 v[42:43], v[42:43], 0, s[36:37]
	v_lshl_add_u64 v[44:45], v[44:45], 0, v[138:139]
	v_lshl_add_u64 v[42:43], v[42:43], 0, v[120:121]
	v_lshlrev_b64 v[44:45], 1, v[44:45]
	v_lshl_add_u64 v[46:47], v[106:107], 0, v[44:45]
	global_load_dwordx4 v[58:61], v[42:43], off
	global_load_dwordx4 v[66:69], v[46:47], off
	v_lshl_add_u64 v[42:43], v[108:109], 0, v[44:45]
	v_add_u32_e32 v44, s41, v156
	v_ashrrev_i32_e32 v45, 31, v44
	v_add_u32_e32 v140, s28, v160
	v_lshlrev_b64 v[44:45], 11, v[44:45]
	v_ashrrev_i32_e32 v141, 31, v140
	v_lshl_add_u64 v[44:45], v[44:45], 0, v[140:141]
	v_lshlrev_b64 v[44:45], 1, v[44:45]
	v_lshl_add_u64 v[46:47], v[106:107], 0, v[44:45]
	global_load_dwordx4 v[74:77], v[42:43], off
	global_load_dwordx4 v[78:81], v[46:47], off
	v_lshl_add_u64 v[42:43], v[108:109], 0, v[44:45]
	v_add_u32_e32 v44, s41, v161
	v_ashrrev_i32_e32 v45, 31, v44
	v_add_u32_e32 v142, s28, v162
	v_lshlrev_b64 v[44:45], 11, v[44:45]
	v_ashrrev_i32_e32 v143, 31, v142
	v_lshl_add_u64 v[44:45], v[44:45], 0, v[142:143]
	v_lshlrev_b64 v[44:45], 1, v[44:45]
	v_lshl_add_u64 v[46:47], v[106:107], 0, v[44:45]
	global_load_dwordx4 v[86:89], v[42:43], off
	global_load_dwordx4 v[90:93], v[46:47], off
	v_lshl_add_u64 v[42:43], v[108:109], 0, v[44:45]
	v_add_u32_e32 v44, s41, v163
	v_ashrrev_i32_e32 v45, 31, v44
	v_add_u32_e32 v144, s28, v164
	v_lshlrev_b64 v[44:45], 11, v[44:45]
	v_ashrrev_i32_e32 v145, 31, v144
	v_lshl_add_u64 v[44:45], v[44:45], 0, v[144:145]
	v_lshlrev_b64 v[44:45], 1, v[44:45]
	v_lshl_add_u64 v[46:47], v[106:107], 0, v[44:45]
	global_load_dwordx4 v[94:97], v[42:43], off
	global_load_dwordx4 v[98:101], v[46:47], off
	v_lshl_add_u64 v[42:43], v[108:109], 0, v[44:45]
	global_load_dwordx4 v[102:105], v[42:43], off
	v_lshl_add_u64 v[38:39], v[38:39], 0, s[34:35]
	v_lshl_add_u64 v[38:39], v[38:39], 0, s[36:37]
	v_lshl_add_u64 v[38:39], v[38:39], 0, s[84:85]
	v_lshlrev_b32_e32 v40, 1, v41
	v_lshl_add_u64 v[132:133], v[38:39], 0, v[0:1]
	v_sub_u32_e32 v38, 63, v149
	v_and_b32_e32 v46, 0x70, v40
	v_and_b32_e32 v47, 14, v40
	v_readlane_b32 s28, v255, 1
	v_cndmask_b32_e64 v38, v38, v149, s[24:25]
	s_movk_i32 s31, 0x220
	v_add3_u32 v48, s28, v46, v47
	v_lshl_add_u64 v[40:41], v[110:111], 0, s[34:35]
	v_mad_u64_u32 v[38:39], s[28:29], v38, s31, v[112:113]
	v_lshl_add_u64 v[40:41], v[40:41], 0, s[36:37]
	v_sub_u32_e32 v39, 63, v156
	v_lshl_add_u64 v[146:147], v[40:41], 0, v[120:121]
	v_sub_u32_e32 v40, 63, v119
	v_cndmask_b32_e64 v39, v39, v156, s[24:25]
	v_cndmask_b32_e64 v176, v40, v119, s[24:25]
	v_mad_u64_u32 v[40:41], s[28:29], v39, s31, v[114:115]
	v_sub_u32_e32 v39, 63, v161
	v_cndmask_b32_e64 v39, v39, v161, s[24:25]
	v_mad_u64_u32 v[42:43], s[28:29], v39, s31, v[116:117]
	v_sub_u32_e32 v39, 63, v163
	v_cndmask_b32_e64 v39, v39, v163, s[24:25]
	v_mad_u64_u32 v[44:45], s[28:29], v39, s31, v[118:119]
	v_add_u32_e32 v41, 0x140, v166
	v_add_u32_e32 v43, 0x280, v166
	v_add_u32_e32 v45, 0x3c0, v166
	v_add_u32_e32 v39, v166, v46
	v_add_u32_e32 v41, v41, v46
	v_add_u32_e32 v43, v43, v46
	v_add_u32_e32 v45, v45, v46
	s_lshl_b32 s30, s40, 12
	v_mov_b32_e32 v131, v130
	v_mov_b32_e32 v134, v130
	v_mov_b32_e32 v135, v130
	v_mov_b32_e32 v123, v122
	v_mov_b32_e32 v126, v122
	v_mov_b32_e32 v127, v122
	v_mov_b32_e32 v125, v124
	v_mov_b32_e32 v128, v124
	v_mov_b32_e32 v129, v124
	v_mov_b32_e32 v137, v136
	s_movk_i32 s35, 0x43
	v_add_u32_e32 v191, 0, v38
	v_add_u32_e32 v190, 0, v40
	v_add_u32_e32 v189, 0, v42
	v_add_u32_e32 v188, 0, v44
	v_add_u32_e32 v177, v48, v165
	v_add_u32_e32 v187, v39, v47
	v_add_u32_e32 v186, v41, v47
	v_add_u32_e32 v185, v43, v47
	v_add_u32_e32 v184, v45, v47
	v_mov_b32_e32 v38, v2
	v_mov_b32_e32 v39, v2
	v_mov_b32_e32 v40, v2
	v_mov_b32_e32 v41, v2
	v_mov_b32_e32 v42, v2
	v_mov_b32_e32 v43, v2
	v_mov_b32_e32 v44, v2
	v_mov_b32_e32 v45, v2
	v_mov_b32_e32 v46, v2
	v_mov_b32_e32 v47, v2
	v_mov_b32_e32 v48, v2
	v_mov_b32_e32 v49, v2
	v_mov_b32_e32 v50, v2
	v_mov_b32_e32 v51, v2
	v_mov_b32_e32 v52, v2
	v_mov_b32_e32 v53, v2
	v_mov_b32_e32 v54, v2
	v_mov_b32_e32 v55, v2
	v_mov_b32_e32 v56, v2
	v_mov_b32_e32 v57, v2
	v_mov_b32_e32 v62, v2
	v_mov_b32_e32 v63, v2
	v_mov_b32_e32 v64, v2
	v_mov_b32_e32 v65, v2
	v_mov_b32_e32 v70, v2
	v_mov_b32_e32 v71, v2
	v_mov_b32_e32 v72, v2
	v_mov_b32_e32 v73, v2
	v_mov_b32_e32 v82, v2
	v_mov_b32_e32 v83, v2
	v_mov_b32_e32 v84, v2
	v_mov_b32_e32 v85, v2
	s_waitcnt vmcnt(7)
	ds_write_b128 v191, v[66:69]
	s_waitcnt vmcnt(6)
	ds_write_b128 v191, v[74:77] offset:34816
	s_waitcnt vmcnt(5)
	ds_write_b128 v190, v[78:81]
	s_waitcnt vmcnt(4)
	ds_write_b128 v190, v[86:89] offset:34816
	s_waitcnt vmcnt(3)
	ds_write_b128 v189, v[90:93]
	s_waitcnt vmcnt(2)
	ds_write_b128 v189, v[94:97] offset:34816
	s_waitcnt vmcnt(1)
	ds_write_b128 v188, v[98:101]
	s_waitcnt vmcnt(0)
	ds_write_b128 v188, v[102:105] offset:34816
;     ...
;             MX_STAGE(u);
;             if (MXP_STG > 1) { asm volatile("" ::: "memory"); MX_STAGE(u); }
;             if (HG) {
;                 MX_BAR();
;                 const int d = tid & 127, qr = tid >> 7;
;                 float cl[16], qv[16], kv[16]; float run = 0.f;
; #pragma unroll
;                 for (int ii = 0; ii < 16; ++ii) { const int s = 16 * qr + ii;
;                     const int eo = s * QS + 16 * ((d >> 3) ^ sw16(s)) + (d & 7) * 2;
;                     run += bflo((unsigned)*(const LAS unsigned short*)(L + 2 * IMG + eo)); cl[ii] = run;
;                     qv[ii] = bflo((unsigned)*(const LAS unsigned short*)(L + eo)); kv[ii] = bflo((unsigned)*(const LAS unsigned short*)(L + IMG + eo)); }
;                 LAS float* tot = (LAS float*)(L + O_TOT);
;                 tot[qr * 128 + d] = run;
;                 MX_BAR();
;                 const float t0 = tot[d], t1 = tot[128 + d], t2 = tot[256 + d], t3 = tot[384 + d];
;                 const float off = (qr == 0) ? 0.f : (qr == 1) ? t0 : (qr == 2) ? (t0 + t1) : (t0 + t1 + t2);
;                 const float cref = t0 + t1, cend = (t0 + t1) + (t2 + t3);
;                 if (qr == 0) tot[512 + d] = cend;
; #pragma unroll
;                 for (int ii = 0; ii < 16; ++ii) { const int s = 16 * qr + ii; const float cm = off + cl[ii]; const int eo = s * QS + 16 * ((d >> 3) ^ sw16(s)) + (d & 7) * 2;
;                     const float e1 = __expf(fminf(cm - cref, 80.f)), e2 = __expf(fminf(cref - cm, 80.f)), e3 = __expf(cm), e4 = __expf(cend - cm);
;                     const unsigned w12 = pk2(qv[ii] * e1, kv[ii] * e2), w34 = pk2(qv[ii] * e3, kv[ii] * e4);
;                     *(LAS unsigned short*)(L + eo) = (unsigned short)(w12 & 0xffffu);
;                     *(LAS unsigned short*)(L + IMG + eo) = (unsigned short)(w12 >> 16);
;                     *(LAS unsigned short*)(L + 2 * IMG + eo) = (unsigned short)(w34 & 0xffffu);
;                     *(LAS unsigned short*)(L + 3 * IMG + eo) = (unsigned short)(w34 >> 16); }
;             }
;             MX_BAR();
;             { const int cn = (c + PF < NCH) ? c + PF : NCH - 1; MX_LOAD(cn, u); }
;             if (MXP_SLEEP > 0) __builtin_amdgcn_s_sleep(MXP_SLEEP);
;             const int rlo = MX_ROWLO(c);
;             const bool do_out = ctx_out || c >= NCTX;
;             mx_bf16x8 aq[KS];
;             if (do_out) {
; #pragma unroll
.LBB0_803:
	s_add_i32 s31, s27, 1
	s_add_i32 s34, s35, -1
	v_sub_co_u32_e64 v178, s[36:37], s27, 3
	s_and_b64 s[28:29], s[24:25], exec
	s_waitcnt vmcnt(0)
	v_lshlrev_b32_e32 v66, 16, v58
	v_and_b32_e32 v67, 0xffff0000, v58
	v_readfirstlane_b32 s28, v178
	v_pk_mul_f32 v[66:67], v[136:137], v[66:67]
	s_cselect_b32 s28, s28, s34
	v_cvt_pk_bf16_f32 v58, v66, v67
	s_lshl_b32 s40, s28, 6
	s_add_i32 s41, s35, 0xffffffbf
	ds_write_b16 v177, v58
	ds_write_b16_d16_hi v187, v58 offset:160
	v_lshlrev_b32_e32 v58, 16, v59
	v_and_b32_e32 v59, 0xffff0000, v59
	s_and_b64 s[28:29], s[24:25], exec
	v_pk_mul_f32 v[58:59], v[136:137], v[58:59]
	s_cselect_b32 s28, s31, s41
	v_cvt_pk_bf16_f32 v58, v58, v59
	s_lshl_b32 s28, s28, 6
	ds_write_b16 v177, v58 offset:320
	ds_write_b16_d16_hi v186, v58 offset:160
	v_lshlrev_b32_e32 v58, 16, v60
	v_and_b32_e32 v59, 0xffff0000, v60
	s_add_i32 s41, s28, s26
	v_pk_mul_f32 v[58:59], v[136:137], v[58:59]
	s_cmp_gt_u32 s27, 3
	v_cvt_pk_bf16_f32 v58, v58, v59
	s_cselect_b64 s[28:29], -1, 0
	ds_write_b16 v177, v58 offset:640
	ds_write_b16_d16_hi v185, v58 offset:160
	v_lshlrev_b32_e32 v58, 16, v61
	v_and_b32_e32 v59, 0xffff0000, v61
	s_add_i32 s40, s40, s30
	v_pk_mul_f32 v[58:59], v[136:137], v[58:59]
	s_and_b64 s[36:37], s[36:37], exec
	v_cvt_pk_bf16_f32 v58, v58, v59
	s_cselect_b32 s36, s41, s40
	ds_write_b16 v177, v58 offset:960
	ds_write_b16_d16_hi v184, v58 offset:160
	v_add_u32_e32 v58, s36, v149
	v_ashrrev_i32_e32 v59, 31, v58
	v_lshlrev_b64 v[58:59], 11, v[58:59]
	v_lshl_add_u64 v[58:59], v[58:59], 0, v[138:139]
	v_lshlrev_b64 v[58:59], 1, v[58:59]
	s_waitcnt lgkmcnt(0)
	s_barrier
	v_lshl_add_u64 v[60:61], v[106:107], 0, v[58:59]
	v_lshl_add_u64 v[58:59], v[108:109], 0, v[58:59]
	global_load_dwordx4 v[66:69], v[60:61], off
	global_load_dwordx4 v[74:77], v[58:59], off
	v_add_u32_e32 v58, s36, v156
	v_ashrrev_i32_e32 v59, 31, v58
	v_lshlrev_b64 v[58:59], 11, v[58:59]
	v_lshl_add_u64 v[58:59], v[58:59], 0, v[140:141]
	v_lshlrev_b64 v[58:59], 1, v[58:59]
	v_lshl_add_u64 v[60:61], v[106:107], 0, v[58:59]
	v_lshl_add_u64 v[58:59], v[108:109], 0, v[58:59]
	global_load_dwordx4 v[78:81], v[60:61], off
	global_load_dwordx4 v[86:89], v[58:59], off
	v_add_u32_e32 v58, s36, v161
	v_ashrrev_i32_e32 v59, 31, v58
	v_lshlrev_b64 v[58:59], 11, v[58:59]
	v_lshl_add_u64 v[58:59], v[58:59], 0, v[142:143]
	v_lshlrev_b64 v[58:59], 1, v[58:59]
	v_lshl_add_u64 v[60:61], v[106:107], 0, v[58:59]
	v_lshl_add_u64 v[58:59], v[108:109], 0, v[58:59]
	global_load_dwordx4 v[90:93], v[60:61], off
	global_load_dwordx4 v[94:97], v[58:59], off
	v_add_u32_e32 v58, s36, v163
	v_ashrrev_i32_e32 v59, 31, v58
	v_lshlrev_b64 v[58:59], 11, v[58:59]
	v_lshl_add_u64 v[58:59], v[58:59], 0, v[144:145]
	v_lshlrev_b64 v[58:59], 1, v[58:59]
	v_lshl_add_u64 v[60:61], v[106:107], 0, v[58:59]
	v_lshl_add_u64 v[58:59], v[108:109], 0, v[58:59]
	global_load_dwordx4 v[98:101], v[60:61], off
	global_load_dwordx4 v[102:105], v[58:59], off
	v_or_b32_e32 v58, s36, v113
	v_ashrrev_i32_e32 v59, 31, v58
	v_lshlrev_b64 v[58:59], 12, v[58:59]
	v_lshl_add_u64 v[58:59], v[146:147], 0, v[58:59]
	global_load_dwordx4 v[58:61], v[58:59], off
	s_or_b64 s[28:29], s[4:5], s[28:29]
	s_and_b64 vcc, exec, s[28:29]
	s_cbranch_vccz .LBB0_805
	v_add_u32_e32 v34, v152, v117
	v_add_u32_e32 v178, v153, v117
	ds_read_b128 v[6:9], v34
	ds_read_b128 v[10:13], v34 offset:64
	ds_read_b128 v[14:17], v34 offset:128
	ds_read_b128 v[18:21], v34 offset:192
	ds_read_b128 v[22:25], v34 offset:256
	ds_read_b128 v[26:29], v34 offset:320
	ds_read_b128 v[30:33], v34 offset:384
	ds_read_b128 v[34:37], v34 offset:448
	ds_read_b128 v[192:195], v178 offset:34816
	ds_read_b128 v[196:199], v178 offset:34880
	ds_read_b128 v[200:203], v178 offset:43520
	ds_read_b128 v[204:207], v178 offset:43584
	ds_read_b128 v[208:211], v178 offset:34944
	ds_read_b128 v[212:215], v178 offset:35008
	ds_read_b128 v[216:219], v178 offset:43648
	ds_read_b128 v[228:231], v178 offset:43712
	s_waitcnt lgkmcnt(7)
	v_mfma_f32_16x16x32_bf16 v[192:195], v[192:195], v[6:9], v[2:5]
	s_waitcnt lgkmcnt(5)
	v_mfma_f32_16x16x32_bf16 v[200:203], v[200:203], v[6:9], v[2:5]
	v_mfma_f32_16x16x32_bf16 v[192:195], v[196:199], v[10:13], v[192:195]
	s_waitcnt lgkmcnt(4)
	v_mfma_f32_16x16x32_bf16 v[196:199], v[204:207], v[10:13], v[200:203]
	s_waitcnt lgkmcnt(3)
	v_mfma_f32_16x16x32_bf16 v[192:195], v[208:211], v[14:17], v[192:195]
	s_waitcnt lgkmcnt(1)
	v_mfma_f32_16x16x32_bf16 v[196:199], v[216:219], v[14:17], v[196:199]
	v_mfma_f32_16x16x32_bf16 v[192:195], v[212:215], v[18:21], v[192:195]
	s_waitcnt lgkmcnt(0)
	v_mfma_f32_16x16x32_bf16 v[196:199], v[228:231], v[18:21], v[196:199]
	ds_read_b128 v[200:203], v178 offset:35072
	ds_read_b128 v[204:207], v178 offset:35136
	ds_read_b128 v[208:211], v178 offset:43776
	ds_read_b128 v[212:215], v178 offset:43840
	ds_read_b128 v[216:219], v178 offset:35200
	ds_read_b128 v[228:231], v178 offset:35264
	ds_read_b128 v[232:235], v178 offset:43904
	ds_read_b128 v[236:239], v178 offset:43968
	s_waitcnt lgkmcnt(7)
	v_mfma_f32_16x16x32_bf16 v[192:195], v[200:203], v[22:25], v[192:195]
	s_waitcnt lgkmcnt(5)
	v_mfma_f32_16x16x32_bf16 v[196:199], v[208:211], v[22:25], v[196:199]
	v_mfma_f32_16x16x32_bf16 v[192:195], v[204:207], v[26:29], v[192:195]
	s_waitcnt lgkmcnt(4)
	v_mfma_f32_16x16x32_bf16 v[196:199], v[212:215], v[26:29], v[196:199]
	s_waitcnt lgkmcnt(3)
	v_mfma_f32_16x16x32_bf16 v[192:195], v[216:219], v[30:33], v[192:195]
	s_waitcnt lgkmcnt(1)
	v_mfma_f32_16x16x32_bf16 v[196:199], v[232:235], v[30:33], v[196:199]
	v_mfma_f32_16x16x32_bf16 v[192:195], v[228:231], v[34:37], v[192:195]
	s_waitcnt lgkmcnt(0)
	v_mfma_f32_16x16x32_bf16 v[196:199], v[236:239], v[34:37], v[196:199]
	s_nop 5
	v_cndmask_b32_e64 v178, v192, 0, s[8:9]
	v_cndmask_b32_e64 v179, 0, v193, s[10:11]
	v_cvt_pk_bf16_f32 v178, v178, v179
	v_cndmask_b32_e64 v179, v194, 0, s[12:13]
	v_cndmask_b32_e64 v180, v195, 0, s[14:15]
	v_cvt_pk_bf16_f32 v179, v179, v180
	v_add_u32_e32 v180, v158, v148
	ds_write_b64 v180, v[178:179]
	v_cndmask_b32_e64 v178, v196, 0, s[16:17]
	v_cndmask_b32_e64 v179, v197, 0, s[18:19]
	v_cvt_pk_bf16_f32 v178, v178, v179
	v_cndmask_b32_e64 v179, v198, 0, s[20:21]
	v_cndmask_b32_e64 v180, v199, 0, s[22:23]
	v_cvt_pk_bf16_f32 v179, v179, v180
	v_add_u32_e32 v180, v159, v148
	ds_write_b64 v180, v[178:179]
; #define LAS __attribute__((address_space(3)))
; #define MX_MFMA(a, b, c) __builtin_amdgcn_mfma_f32_16x16x32_bf16((a), (b), (c), 0, 0, 0)
; #define MX_BAR() do { asm volatile("s_waitcnt lgkmcnt(0)" ::: "memory"); __builtin_amdgcn_s_barrier(); if (MXP_BAR > 1) __builtin_amdgcn_s_barrier(); asm volatile("" ::: "memory"); } while (0)
;     ...
;             {
;                 mx_bf16x8 vt[4][2], ak[DT][2]; f32x4 dec[DT];
; #pragma unroll
;                 for (int te = 0; te < 4; ++te) { vt[te][0] = frag_row8(L + O_VT, 16 * te, 0, lane); vt[te][1] = frag_row8(L + O_VT, 16 * te, 32, lane); }
; #pragma unroll
;                 for (int td = 0; td < DT; ++td) { const int d0 = 16 * (DT * w + td);
;                     ak[td][0] = frag_tr(L + (HG ? 3 : 1) * IMG, QS, 0, d0, lane); ak[td][1] = frag_tr(L + (HG ? 3 : 1) * IMG, QS, 32, d0, lane);
;                     dec[td] = (f32x4){cdec, cdec, cdec, cdec};
;                     if (HG) { const f32x4 ce = *(const LAS f32x4*)(L + O_TOT + 2048 + (d0 + 4 * g) * 4); dec[td] = (f32x4){__expf(ce[0]), __expf(ce[1]), __expf(ce[2]), __expf(ce[3])}; } }
;                 __builtin_amdgcn_sched_barrier(0);
; #pragma unroll
;                 for (int td = 0; td < DT; ++td)
; #pragma unroll
;                     for (int te = 0; te < 4; ++te) accS[td][te] = MX_MFMA(ak[td][0], vt[te][0], accS[td][te] * dec[td]);
; #pragma unroll
;                 for (int td = 0; td < DT; ++td)
; #pragma unroll
;                     for (int te = 0; te < 4; ++te) accS[td][te] = MX_MFMA(ak[td][1], vt[te][1], accS[td][te]);
;             }
;             MX_BAR();
;             if (do_out) {
;                 if (HG) {
; #pragma unroll
;                     for (int ks = 0; ks < KS; ++ks) aq[ks] = frag_row(L + 2 * IMG, QS, nq0, 32 * ks, lane);
;                 }
;                 mx_bf16x8 vo[2][2];
;                 const mx_bf16x8 bp0 = frag_row8(L + O_P, nq0, 0, lane), bp1 = frag_row8(L + O_P, nq0, 32, lane);
; #pragma unroll
;                 for (int te = 0; te < 2; ++te) { vo[te][0] = frag_row8(L + O_VT, 32 * cg + 16 * te, 0, lane); vo[te][1] = frag_row8(L + O_VT, 32 * cg + 16 * te, 32, lane); }
.LBB0_805:
	v_add_u32_e32 v192, v167, v117
	ds_read_b128 v[194:197], v192
	ds_read_b128 v[198:201], v192 offset:64
	ds_read_b128 v[202:205], v171
	ds_read_b128 v[206:209], v171 offset:64
	ds_read_b128 v[210:213], v172
	ds_read_b128 v[214:217], v172 offset:64
	ds_read_b128 v[228:231], v173
	ds_read_b128 v[232:235], v173 offset:64
	ds_read_b64_tr_b16 v[236:237], v174 offset:34816
	ds_read_b64_tr_b16 v[238:239], v174 offset:36992
	ds_read_b64_tr_b16 v[242:243], v174 offset:37024
	ds_read_b64_tr_b16 v[240:241], v174 offset:34848
	ds_read_b64_tr_b16 v[244:245], v174 offset:52224
	ds_read_b64_tr_b16 v[246:247], v174 offset:54400
	ds_read_b64_tr_b16 v[250:251], v174 offset:54432
	ds_read_b64_tr_b16 v[248:249], v174 offset:52256
	v_pk_mul_f32 v[84:85], v[134:135], v[84:85]
	v_pk_mul_f32 v[82:83], v[130:131], v[82:83]
	v_pk_mul_f32 v[72:73], v[134:135], v[72:73]
	v_pk_mul_f32 v[70:71], v[130:131], v[70:71]
	v_pk_mul_f32 v[64:65], v[134:135], v[64:65]
	v_pk_mul_f32 v[62:63], v[130:131], v[62:63]
	v_pk_mul_f32 v[56:57], v[134:135], v[56:57]
	v_pk_mul_f32 v[54:55], v[130:131], v[54:55]
	v_pk_mul_f32 v[52:53], v[134:135], v[52:53]
	v_pk_mul_f32 v[50:51], v[130:131], v[50:51]
	v_pk_mul_f32 v[48:49], v[134:135], v[48:49]
	v_pk_mul_f32 v[46:47], v[130:131], v[46:47]
	v_pk_mul_f32 v[44:45], v[134:135], v[44:45]
	v_pk_mul_f32 v[42:43], v[130:131], v[42:43]
	v_pk_mul_f32 v[40:41], v[134:135], v[40:41]
	v_pk_mul_f32 v[38:39], v[130:131], v[38:39]
	s_waitcnt lgkmcnt(6)
	v_mfma_f32_16x16x32_bf16 v[82:85], v[236:239], v[194:197], v[82:85]
	s_waitcnt lgkmcnt(0)
	s_barrier
	v_mfma_f32_16x16x32_bf16 v[70:73], v[236:239], v[202:205], v[70:73]
	s_andn2_b64 vcc, exec, s[28:29]
	v_mfma_f32_16x16x32_bf16 v[62:65], v[236:239], v[210:213], v[62:65]
	v_mfma_f32_16x16x32_bf16 v[54:57], v[236:239], v[228:231], v[54:57]
	s_waitcnt lgkmcnt(4)
	v_mfma_f32_16x16x32_bf16 v[50:53], v[240:243], v[194:197], v[50:53]
	v_mfma_f32_16x16x32_bf16 v[46:49], v[240:243], v[202:205], v[46:49]
	v_mfma_f32_16x16x32_bf16 v[42:45], v[240:243], v[210:213], v[42:45]
	v_mfma_f32_16x16x32_bf16 v[38:41], v[240:243], v[228:231], v[38:41]
	s_waitcnt lgkmcnt(2)
	v_mfma_f32_16x16x32_bf16 v[82:85], v[244:247], v[198:201], v[82:85]
	v_mfma_f32_16x16x32_bf16 v[70:73], v[244:247], v[206:209], v[70:73]
	v_mfma_f32_16x16x32_bf16 v[62:65], v[244:247], v[214:217], v[62:65]
	v_mfma_f32_16x16x32_bf16 v[54:57], v[244:247], v[232:235], v[54:57]
	s_waitcnt lgkmcnt(0)
	v_mfma_f32_16x16x32_bf16 v[50:53], v[248:251], v[198:201], v[50:53]
	v_mfma_f32_16x16x32_bf16 v[46:49], v[248:251], v[206:209], v[46:49]
	v_mfma_f32_16x16x32_bf16 v[42:45], v[248:251], v[214:217], v[42:45]
	v_mfma_f32_16x16x32_bf16 v[38:41], v[248:251], v[232:235], v[38:41]
	s_cbranch_vccnz ret_stage_skip
; #define GAS __attribute__((address_space(1)))
; __device__ __forceinline__ unsigned pk2(float lo, float hi) { const f32x2_t v = {lo, hi}; const bf16x2_t b = __builtin_convertvector(v, bf16x2_t); return __builtin_bit_cast(unsigned, b); }
; #define MX_MFMA(a, b, c) __builtin_amdgcn_mfma_f32_16x16x32_bf16((a), (b), (c), 0, 0, 0)
;     ...
;             if (do_out) {
;                 if (HG) {
; #pragma unroll
;                     for (int ks = 0; ks < KS; ++ks) aq[ks] = frag_row(L + 2 * IMG, QS, nq0, 32 * ks, lane);
;                 }
;                 mx_bf16x8 vo[2][2];
;                 const mx_bf16x8 bp0 = frag_row8(L + O_P, nq0, 0, lane), bp1 = frag_row8(L + O_P, nq0, 32, lane);
; #pragma unroll
;                 for (int te = 0; te < 2; ++te) { vo[te][0] = frag_row8(L + O_VT, 32 * cg + 16 * te, 0, lane); vo[te][1] = frag_row8(L + O_VT, 32 * cg + 16 * te, 32, lane); }
;                 const int grow = rlo + (dir ? 63 - (nq0 + i) : (nq0 + i));
;                 for (int rep2 = 0; rep2 < MXP_S2; ++rep2) {
;                 f32x4 o1a = ZERO4, o1b = o1a, o2a = o1a, o2b = o1a;
; #pragma unroll
;                 for (int kb = 0; kb < KS; kb += 4) {
;                     mx_bf16x8 st[2][4];
; #pragma unroll
;                     for (int ks = 0; ks < 4; ++ks) { st[0][ks] = frag_row(L + O_ST, QS, 32 * cg, 32 * (kb + ks), lane); st[1][ks] = frag_row(L + O_ST, QS, 32 * cg + 16, 32 * (kb + ks), lane); }
;                     __builtin_amdgcn_sched_barrier(0);
;                     if (kb == 0) { o1a = MX_MFMA(vo[0][0], bp0, o1a); o1b = MX_MFMA(vo[1][0], bp0, o1b); o1a = MX_MFMA(vo[0][1], bp1, o1a); o1b = MX_MFMA(vo[1][1], bp1, o1b); }
; #pragma unroll
;                     for (int ks = 0; ks < 4; ++ks) { o2a = MX_MFMA(st[0][ks], aq[kb + ks], o2a); o2b = MX_MFMA(st[1][ks], aq[kb + ks], o2b); }
;                     __builtin_amdgcn_sched_barrier(0);
;                 }
;                 bf16* op = O + (size_t)grow * D + h * HD + eb * 64 + 32 * cg + 4 * g;
;                 if (!(VAR & 2)) { const f32x4 ya = o1a * r1 + o2a * r2, yb = o1b * r1 + o2b * r2; v2u wa, wb; wa.x = pk2(ya[0], ya[1]); wa.y = pk2(ya[2], ya[3]); wb.x = pk2(yb[0], yb[1]); wb.y = pk2(yb[2], yb[3]);
;                     *(GAS v2u*)(op) = wa; *(GAS v2u*)(op + 16) = wb; }
;                 else { asm volatile("" :: "v"(o1a), "v"(o1b), "v"(o2a), "v"(o2b)); }
	v_sub_co_u32_e64 v178, s[28:29], s27, 4
	s_and_b64 s[36:37], s[24:25], exec
	v_readfirstlane_b32 s36, v178
	s_cselect_b32 s36, s36, s35
	s_lshl_b32 s40, s36, 6
	s_sub_i32 s35, s35, 64
	s_and_b64 s[36:37], s[24:25], exec
	s_cselect_b32 s27, s27, s35
	s_lshl_b32 s27, s27, 6
	s_add_i32 s27, s27, s26
	s_add_i32 s40, s40, s30
	s_and_b64 s[28:29], s[28:29], exec
	v_add_u32_e32 v178, v154, v117
	s_cselect_b32 s27, s27, s40
	ds_read_b128 v[194:197], v178
	ds_read_b128 v[198:201], v178 offset:64
	v_add_u32_e32 v178, v168, v117
	ds_read_b128 v[202:205], v178
	ds_read_b128 v[206:209], v178 offset:64
	ds_read_b128 v[210:213], v178 offset:2560
	ds_read_b128 v[214:217], v178 offset:2624
	v_add_u32_e32 v178, s27, v176
	v_ashrrev_i32_e32 v179, 31, v178
	v_lshlrev_b64 v[178:179], 12, v[178:179]
	v_add_u32_e32 v193, v155, v117
	v_lshl_add_u64 v[218:219], v[132:133], 0, v[178:179]
	ds_read_b128 v[228:231], v193
	ds_read_b128 v[232:235], v193 offset:8704
	ds_read_b128 v[236:239], v193 offset:64
	ds_read_b128 v[240:243], v193 offset:8768
	ds_read_b128 v[244:247], v193 offset:128
	ds_read_b128 v[248:251], v193 offset:8832
	ds_read_b128 v[178:181], v193 offset:192
	ds_read_b128 v[224:227], v193 offset:8896
	s_waitcnt lgkmcnt(11)
	v_mfma_f32_16x16x32_bf16 v[202:205], v[202:205], v[194:197], v[2:5]
	s_waitcnt lgkmcnt(9)
	v_mfma_f32_16x16x32_bf16 v[194:197], v[210:213], v[194:197], v[2:5]
	v_mfma_f32_16x16x32_bf16 v[202:205], v[206:209], v[198:201], v[202:205]
	s_waitcnt lgkmcnt(8)
	v_mfma_f32_16x16x32_bf16 v[194:197], v[214:217], v[198:201], v[194:197]
	s_waitcnt lgkmcnt(7)
	v_mfma_f32_16x16x32_bf16 v[198:201], v[228:231], v[6:9], v[2:5]
	s_waitcnt lgkmcnt(6)
	v_mfma_f32_16x16x32_bf16 v[206:209], v[232:235], v[6:9], v[2:5]
	s_waitcnt lgkmcnt(5)
	v_mfma_f32_16x16x32_bf16 v[198:201], v[236:239], v[10:13], v[198:201]
	s_waitcnt lgkmcnt(4)
	v_mfma_f32_16x16x32_bf16 v[206:209], v[240:243], v[10:13], v[206:209]
	s_waitcnt lgkmcnt(3)
	v_mfma_f32_16x16x32_bf16 v[198:201], v[244:247], v[14:17], v[198:201]
	s_waitcnt lgkmcnt(2)
	v_mfma_f32_16x16x32_bf16 v[206:209], v[248:251], v[14:17], v[206:209]
	s_waitcnt lgkmcnt(1)
	v_mfma_f32_16x16x32_bf16 v[178:181], v[178:181], v[18:21], v[198:201]
	s_waitcnt lgkmcnt(0)
	v_mfma_f32_16x16x32_bf16 v[198:201], v[224:227], v[18:21], v[206:209]
	s_nop 3
	ds_read_b128 v[206:209], v193 offset:256
	ds_read_b128 v[210:213], v193 offset:320
	ds_read_b128 v[214:217], v193 offset:8960
	ds_read_b128 v[224:227], v193 offset:9024
	ds_read_b128 v[228:231], v193 offset:384
	ds_read_b128 v[232:235], v193 offset:448
	ds_read_b128 v[236:239], v193 offset:9088
	ds_read_b128 v[240:243], v193 offset:9152
	s_waitcnt lgkmcnt(7)
	v_mfma_f32_16x16x32_bf16 v[178:181], v[206:209], v[22:25], v[178:181]
	s_waitcnt lgkmcnt(5)
	v_mfma_f32_16x16x32_bf16 v[198:201], v[214:217], v[22:25], v[198:201]
	v_mfma_f32_16x16x32_bf16 v[178:181], v[210:213], v[26:29], v[178:181]
	s_waitcnt lgkmcnt(4)
	v_mfma_f32_16x16x32_bf16 v[198:201], v[224:227], v[26:29], v[198:201]
	s_waitcnt lgkmcnt(3)
	v_mfma_f32_16x16x32_bf16 v[178:181], v[228:231], v[30:33], v[178:181]
	s_waitcnt lgkmcnt(1)
	v_mfma_f32_16x16x32_bf16 v[198:201], v[236:239], v[30:33], v[198:201]
	v_mfma_f32_16x16x32_bf16 v[178:181], v[232:235], v[34:37], v[178:181]
	s_waitcnt lgkmcnt(0)
	v_mfma_f32_16x16x32_bf16 v[198:201], v[240:243], v[34:37], v[198:201]
	s_waitcnt vmcnt(8)
	ds_write_b128 v191, v[66:69]
	s_waitcnt vmcnt(7)
	ds_write_b128 v191, v[74:77] offset:34816
	s_waitcnt vmcnt(6)
	ds_write_b128 v190, v[78:81]
	s_waitcnt vmcnt(5)
	ds_write_b128 v190, v[86:89] offset:34816
	s_waitcnt vmcnt(4)
	ds_write_b128 v189, v[90:93]
	s_waitcnt vmcnt(3)
	ds_write_b128 v189, v[94:97] offset:34816
	s_waitcnt vmcnt(2)
	ds_write_b128 v188, v[98:101]
	s_waitcnt vmcnt(1)
	ds_write_b128 v188, v[102:105] offset:34816
	s_nop 5
	v_mul_f32_e64 v180, v128, v180
	v_mul_f32_e64 v181, v129, v181
	v_pk_mul_f32 v[178:179], v[124:125], v[178:179]
	v_pk_fma_f32 v[180:181], v[126:127], v[204:205], v[180:181]
	v_pk_fma_f32 v[178:179], v[122:123], v[202:203], v[178:179]
	v_pk_mul_f32 v[200:201], v[128:129], v[200:201]
	v_pk_mul_f32 v[198:199], v[124:125], v[198:199]
	v_pk_fma_f32 v[196:197], v[126:127], v[196:197], v[200:201]
	v_pk_fma_f32 v[194:195], v[122:123], v[194:195], v[198:199]
	v_cvt_pk_bf16_f32 v178, v178, v179
	v_cvt_pk_bf16_f32 v179, v180, v181
	v_cvt_pk_bf16_f32 v180, v194, v195
	v_cvt_pk_bf16_f32 v181, v196, v197
	global_store_dwordx2 v[218:219], v[178:179], off
	global_store_dwordx2 v[218:219], v[180:181], off offset:32

ret_stage_skip:
	s_waitcnt vmcnt(8)
	ds_write_b128 v191, v[66:69]
	s_waitcnt vmcnt(7)
	ds_write_b128 v191, v[74:77] offset:34816
	s_waitcnt vmcnt(6)
	ds_write_b128 v190, v[78:81]
	s_waitcnt vmcnt(5)
	ds_write_b128 v190, v[86:89] offset:34816
	s_waitcnt vmcnt(4)
	ds_write_b128 v189, v[90:93]
	s_waitcnt vmcnt(3)
	ds_write_b128 v189, v[94:97] offset:34816
	s_waitcnt vmcnt(2)
	ds_write_b128 v188, v[98:101]
	s_waitcnt vmcnt(1)
	ds_write_b128 v188, v[102:105] offset:34816
	s_branch .LBB0_807
